# S5 item BT3 stage: C.lambda pieces rewritten (two packed ops and a select per product, all eight LDS reads up front)
# speedup vs baseline: 1.0035x; 1.0001x over previous
.Lbt3_idx:
	v_lshlrev_b32_e32 v6, 5, v5
	v_add_u32_e32 v5, s86, v5
	v_lshlrev_b32_e32 v4, 3, v51
	v_lshrrev_b32_e32 v52, 4, v5
	v_bfe_u32 v53, v6, 5, 4
	v_and_b32_e32 v13, 7, v53
	v_lshlrev_b32_e32 v13, 4, v13
	v_cmp_lt_u32_e32 vcc, 31, v51
	s_and_saveexec_b64 s[4:5], vcc
	s_xor_b64 s[4:5], exec, s[4:5]
	s_cbranch_execz .Lssa_495
	v_and_b32_e32 v44, 56, v4
	v_lshl_add_u32 v62, v53, 9, 0
	v_lshl_add_u32 v63, v52, 6, 64
	v_and_b32_e32 v8, 56, v51
	v_cmp_eq_u32_e32 vcc, 32, v8
	v_lshl_add_u32 v6, v44, 3, v62
	v_xor_b32_e32 v6, v13, v6
	v_or_b32_e32 v7, v63, v44
	v_lshlrev_b32_e32 v7, 3, v7
	v_xor_b32_e32 v37, 16, v6
	v_xor_b32_e32 v48, 32, v6
	v_xor_b32_e32 v49, 48, v6
	ds_read_b128 v[52:55], v6 offset:16896
	ds_read_b128 v[86:89], v7
	ds_read_b128 v[56:59], v37 offset:16896
	ds_read_b128 v[90:93], v7 offset:16
	ds_read_b128 v[60:63], v48 offset:16896
	ds_read_b128 v[94:97], v7 offset:32
	ds_read_b128 v[82:85], v49 offset:16896
	ds_read_b128 v[98:101], v7 offset:48
	s_waitcnt lgkmcnt(6)
	v_pk_mul_f32 v[102:103], v[52:53], v[86:87] op_sel:[1,1] op_sel_hi:[0,1]
	v_pk_fma_f32 v[102:103], v[52:53], v[86:87], v[102:103] op_sel_hi:[1,0,1] neg_lo:[0,0,1]
	v_pk_mul_f32 v[104:105], v[54:55], v[88:89] op_sel:[1,1] op_sel_hi:[0,1]
	v_pk_fma_f32 v[104:105], v[54:55], v[88:89], v[104:105] op_sel_hi:[1,0,1] neg_lo:[0,0,1]
	v_cndmask_b32_e64 v7, -v103, v102, vcc
	v_cndmask_b32_e64 v6, -v105, v104, vcc
	s_waitcnt lgkmcnt(4)
	v_pk_mul_f32 v[102:103], v[56:57], v[90:91] op_sel:[1,1] op_sel_hi:[0,1]
	v_pk_fma_f32 v[102:103], v[56:57], v[90:91], v[102:103] op_sel_hi:[1,0,1] neg_lo:[0,0,1]
	v_pk_mul_f32 v[104:105], v[58:59], v[92:93] op_sel:[1,1] op_sel_hi:[0,1]
	v_pk_fma_f32 v[104:105], v[58:59], v[92:93], v[104:105] op_sel_hi:[1,0,1] neg_lo:[0,0,1]
	v_cndmask_b32_e64 v37, -v103, v102, vcc
	v_cndmask_b32_e64 v8, -v105, v104, vcc
	s_waitcnt lgkmcnt(2)
	v_pk_mul_f32 v[102:103], v[60:61], v[94:95] op_sel:[1,1] op_sel_hi:[0,1]
	v_pk_fma_f32 v[102:103], v[60:61], v[94:95], v[102:103] op_sel_hi:[1,0,1] neg_lo:[0,0,1]
	v_pk_mul_f32 v[104:105], v[62:63], v[96:97] op_sel:[1,1] op_sel_hi:[0,1]
	v_pk_fma_f32 v[104:105], v[62:63], v[96:97], v[104:105] op_sel_hi:[1,0,1] neg_lo:[0,0,1]
	v_cndmask_b32_e64 v48, -v103, v102, vcc
	v_cndmask_b32_e64 v44, -v105, v104, vcc
	s_waitcnt lgkmcnt(0)
	v_pk_mul_f32 v[102:103], v[82:83], v[98:99] op_sel:[1,1] op_sel_hi:[0,1]
	v_pk_fma_f32 v[102:103], v[82:83], v[98:99], v[102:103] op_sel_hi:[1,0,1] neg_lo:[0,0,1]
	v_pk_mul_f32 v[104:105], v[84:85], v[100:101] op_sel:[1,1] op_sel_hi:[0,1]
	v_pk_fma_f32 v[104:105], v[84:85], v[100:101], v[104:105] op_sel_hi:[1,0,1] neg_lo:[0,0,1]
	v_cndmask_b32_e64 v49, -v103, v102, vcc
	v_cndmask_b32_e64 v50, -v105, v104, vcc
